# second resid GEMM instance (hyout, still hipcc's register-staged loop) moved to the 3-stage LDS-DMA ring
# speedup vs baseline: 1.0117x; 1.0117x over previous
.LBB0_424:
	s_ashr_i32 s22, s1, 31
	s_lshr_b32 s22, s22, 27
	s_add_i32 s22, s1, s22
	s_and_b32 s23, s22, 0xffffe0
	s_sub_i32 s23, s1, s23
	s_lshl_b32 s40, s23, 8
	s_lshl_b32 s22, s22, 2
	s_ashr_i32 s41, s40, 31
	s_and_b32 s42, s22, 0xffffff80
	s_ashr_i32 s43, s42, 31
	s_lshl_b64 s[22:23], s[40:41], 11
	s_add_u32 s22, s6, s22
	s_addc_u32 s23, s7, s23
	s_lshl_b64 s[4:5], s[42:43], 11
	s_add_u32 s4, s24, s4
	s_addc_u32 s5, s21, s5
	s_waitcnt lgkmcnt(0)
	v_lshrrev_b32_e32 v132, 3, v196
	v_lshrrev_b32_e32 v133, 4, v196
	v_xor_b32_e32 v133, v133, v196
	v_and_b32_e32 v133, 7, v133
	v_lshlrev_b32_e32 v133, 4, v133
	v_lshl_or_b32 v82, v132, 11, v133
	v_add_u32_e32 v83, 0x20000, v82
	v_add_u32_e32 v84, 0x40000, v82
	v_add_u32_e32 v85, 0x60000, v82
	v_add_u32_e32 v132, 0, v140
	v_xor_b32_e32 v132, v132, v141
	v_lshlrev_b32_e32 v132, 4, v132
	v_add3_u32 v86, v150, v132, 0
	v_add3_u32 v128, v151, v132, 0
	v_add_u32_e32 v132, 2, v140
	v_xor_b32_e32 v132, v132, v141
	v_lshlrev_b32_e32 v132, 4, v132
	v_add3_u32 v87, v150, v132, 0
	v_add3_u32 v129, v151, v132, 0
	v_add_u32_e32 v132, 4, v140
	v_xor_b32_e32 v132, v132, v141
	v_lshlrev_b32_e32 v132, 4, v132
	v_add3_u32 v88, v150, v132, 0
	v_add3_u32 v130, v151, v132, 0
	v_add_u32_e32 v132, 6, v140
	v_xor_b32_e32 v132, v132, v141
	v_lshlrev_b32_e32 v132, 4, v132
	v_add3_u32 v89, v150, v132, 0
	v_add3_u32 v131, v151, v132, 0
	v_lshrrev_b32_e32 v132, 6, v196
	v_mov_b64_e32 v[2:3], 0
	v_mov_b64_e32 v[4:5], 0
	v_mov_b64_e32 v[6:7], 0
	v_mov_b64_e32 v[8:9], 0
	v_mov_b64_e32 v[10:11], 0
	v_mov_b64_e32 v[12:13], 0
	v_mov_b64_e32 v[14:15], 0
	v_mov_b64_e32 v[16:17], 0
	v_mov_b64_e32 v[18:19], 0
	v_mov_b64_e32 v[20:21], 0
	v_mov_b64_e32 v[22:23], 0
	v_mov_b64_e32 v[24:25], 0
	v_mov_b64_e32 v[26:27], 0
	v_mov_b64_e32 v[28:29], 0
	v_mov_b64_e32 v[30:31], 0
	v_mov_b64_e32 v[32:33], 0
	v_mov_b64_e32 v[34:35], 0
	v_mov_b64_e32 v[36:37], 0
	v_mov_b64_e32 v[38:39], 0
	v_mov_b64_e32 v[40:41], 0
	v_mov_b64_e32 v[42:43], 0
	v_mov_b64_e32 v[44:45], 0
	v_mov_b64_e32 v[46:47], 0
	v_mov_b64_e32 v[48:49], 0
	v_mov_b64_e32 v[50:51], 0
	v_mov_b64_e32 v[52:53], 0
	v_mov_b64_e32 v[54:55], 0
	v_mov_b64_e32 v[56:57], 0
	v_mov_b64_e32 v[58:59], 0
	v_mov_b64_e32 v[60:61], 0
	v_mov_b64_e32 v[62:63], 0
	v_mov_b64_e32 v[64:65], 0
	v_readfirstlane_b32 s26, v132
	s_lshl_b32 s26, s26, 10
	s_add_i32 s26, s26, 16
	s_add_i32 vcc_hi, s26, 0xc000
	s_mov_b32 m0, s26
	s_nop 0
	global_load_lds_dwordx4 v82, s[22:23]
	s_add_u32 m0, m0, 0x2000
	s_nop 0
	global_load_lds_dwordx4 v83, s[22:23]
	s_add_u32 m0, m0, 0x2000
	s_nop 0
	global_load_lds_dwordx4 v84, s[22:23]
	s_add_u32 m0, m0, 0x2000
	s_nop 0
	global_load_lds_dwordx4 v85, s[22:23]
	s_add_u32 m0, m0, 0x2000
	s_nop 0
	global_load_lds_dwordx4 v82, s[4:5]
	s_add_u32 m0, m0, 0x2000
	s_nop 0
	global_load_lds_dwordx4 v83, s[4:5]
	s_add_u32 s22, s22, 0x80
	s_addc_u32 s23, s23, 0
	s_add_u32 s4, s4, 0x80
	s_addc_u32 s5, s5, 0
	s_mov_b32 m0, vcc_hi
	s_nop 0
	global_load_lds_dwordx4 v82, s[22:23]
	s_add_u32 m0, m0, 0x2000
	s_nop 0
	global_load_lds_dwordx4 v83, s[22:23]
	s_add_u32 m0, m0, 0x2000
	s_nop 0
	global_load_lds_dwordx4 v84, s[22:23]
	s_add_u32 m0, m0, 0x2000
	s_nop 0
	global_load_lds_dwordx4 v85, s[22:23]
	s_add_u32 m0, m0, 0x2000
	s_nop 0
	global_load_lds_dwordx4 v82, s[4:5]
	s_add_u32 m0, m0, 0x2000
	s_nop 0
	global_load_lds_dwordx4 v83, s[4:5]
	s_add_u32 s22, s22, 0x80
	s_addc_u32 s23, s23, 0
	s_add_u32 s4, s4, 0x80
	s_addc_u32 s5, s5, 0
	s_mov_b32 s20, 0
	s_movk_i32 s25, 14
.Lres2_loop:
	s_waitcnt vmcnt(6)
	s_barrier
	s_add_i32 vcc_hi, s20, 2
	s_cmp_ge_u32 vcc_hi, 3
	s_cselect_b32 vcc_lo, 3, 0
	s_sub_i32 vcc_hi, vcc_hi, vcc_lo
	s_mul_i32 vcc_hi, vcc_hi, 0xc000
	s_add_i32 vcc_hi, vcc_hi, s26
	ds_read_b128 v[154:157], v86
	ds_read_b128 v[158:161], v86 offset:4096
	ds_read_b128 v[162:165], v128 offset:32768
	ds_read_b128 v[166:169], v128 offset:36864
	ds_read_b128 v[66:69], v87
	ds_read_b128 v[70:73], v87 offset:4096
	ds_read_b128 v[74:77], v129 offset:32768
	ds_read_b128 v[78:81], v129 offset:36864
	s_waitcnt lgkmcnt(4)
	s_setprio 1
	v_mfma_f32_32x32x16_bf16 v[50:65], v[154:157], v[162:165], v[50:65]
	s_mov_b32 m0, vcc_hi
	v_mfma_f32_32x32x16_bf16 v[18:33], v[158:161], v[162:165], v[18:33]
	global_load_lds_dwordx4 v82, s[22:23]
	s_add_u32 m0, m0, 0x2000
	v_mfma_f32_32x32x16_bf16 v[34:49], v[154:157], v[166:169], v[34:49]
	global_load_lds_dwordx4 v83, s[22:23]
	s_add_u32 m0, m0, 0x2000
	v_mfma_f32_32x32x16_bf16 v[2:17], v[158:161], v[166:169], v[2:17]
	global_load_lds_dwordx4 v84, s[22:23]
	s_add_u32 m0, m0, 0x2000
	s_nop 0
	global_load_lds_dwordx4 v85, s[22:23]
	s_add_u32 m0, m0, 0x2000
	s_nop 0
	global_load_lds_dwordx4 v82, s[4:5]
	s_add_u32 m0, m0, 0x2000
	s_nop 0
	global_load_lds_dwordx4 v83, s[4:5]
	s_add_u32 s22, s22, 0x80
	s_addc_u32 s23, s23, 0
	s_add_u32 s4, s4, 0x80
	s_addc_u32 s5, s5, 0
	s_setprio 0
	ds_read_b128 v[154:157], v88
	ds_read_b128 v[158:161], v88 offset:4096
	ds_read_b128 v[162:165], v130 offset:32768
	ds_read_b128 v[166:169], v130 offset:36864
	s_waitcnt lgkmcnt(4)
	s_setprio 1
	v_mfma_f32_32x32x16_bf16 v[50:65], v[66:69], v[74:77], v[50:65]
	v_mfma_f32_32x32x16_bf16 v[18:33], v[70:73], v[74:77], v[18:33]
	v_mfma_f32_32x32x16_bf16 v[34:49], v[66:69], v[78:81], v[34:49]
	v_mfma_f32_32x32x16_bf16 v[2:17], v[70:73], v[78:81], v[2:17]
	s_setprio 0
	ds_read_b128 v[66:69], v89
	ds_read_b128 v[70:73], v89 offset:4096
	ds_read_b128 v[74:77], v131 offset:32768
	ds_read_b128 v[78:81], v131 offset:36864
	s_waitcnt lgkmcnt(4)
	s_setprio 1
	v_mfma_f32_32x32x16_bf16 v[50:65], v[154:157], v[162:165], v[50:65]
	v_mfma_f32_32x32x16_bf16 v[18:33], v[158:161], v[162:165], v[18:33]
	v_mfma_f32_32x32x16_bf16 v[34:49], v[154:157], v[166:169], v[34:49]
	v_mfma_f32_32x32x16_bf16 v[2:17], v[158:161], v[166:169], v[2:17]
	s_setprio 0
	s_waitcnt lgkmcnt(0)
	s_setprio 1
	v_mfma_f32_32x32x16_bf16 v[50:65], v[66:69], v[74:77], v[50:65]
	v_mfma_f32_32x32x16_bf16 v[18:33], v[70:73], v[74:77], v[18:33]
	v_mfma_f32_32x32x16_bf16 v[34:49], v[66:69], v[78:81], v[34:49]
	v_mfma_f32_32x32x16_bf16 v[2:17], v[70:73], v[78:81], v[2:17]
	s_setprio 0
	s_add_i32 s20, s20, 1
	s_cmp_eq_u32 s20, 3
	s_cselect_b32 vcc_lo, 0xfffdc000, 0
	s_cselect_b32 s20, 0, s20
	s_add_i32 vcc_lo, vcc_lo, 0xc000
	v_add_u32_e32 v86, vcc_lo, v86
	v_add_u32_e32 v128, vcc_lo, v128
	v_add_u32_e32 v87, vcc_lo, v87
	v_add_u32_e32 v129, vcc_lo, v129
	v_add_u32_e32 v88, vcc_lo, v88
	v_add_u32_e32 v130, vcc_lo, v130
	v_add_u32_e32 v89, vcc_lo, v89
	v_add_u32_e32 v131, vcc_lo, v131
	s_add_i32 s25, s25, -1
	s_cmp_lg_u32 s25, 0
	s_cbranch_scc1 .Lres2_loop
	s_waitcnt vmcnt(6)
	s_barrier
	ds_read_b128 v[154:157], v86
	ds_read_b128 v[158:161], v86 offset:4096
	ds_read_b128 v[162:165], v128 offset:32768
	ds_read_b128 v[166:169], v128 offset:36864
	ds_read_b128 v[66:69], v87
	ds_read_b128 v[70:73], v87 offset:4096
	ds_read_b128 v[74:77], v129 offset:32768
	ds_read_b128 v[78:81], v129 offset:36864
	s_waitcnt lgkmcnt(4)
	s_setprio 1
	v_mfma_f32_32x32x16_bf16 v[50:65], v[154:157], v[162:165], v[50:65]
	v_mfma_f32_32x32x16_bf16 v[18:33], v[158:161], v[162:165], v[18:33]
	v_mfma_f32_32x32x16_bf16 v[34:49], v[154:157], v[166:169], v[34:49]
	v_mfma_f32_32x32x16_bf16 v[2:17], v[158:161], v[166:169], v[2:17]
	s_setprio 0
	ds_read_b128 v[154:157], v88
	ds_read_b128 v[158:161], v88 offset:4096
	ds_read_b128 v[162:165], v130 offset:32768
	ds_read_b128 v[166:169], v130 offset:36864
	s_waitcnt lgkmcnt(4)
	s_setprio 1
	v_mfma_f32_32x32x16_bf16 v[50:65], v[66:69], v[74:77], v[50:65]
	v_mfma_f32_32x32x16_bf16 v[18:33], v[70:73], v[74:77], v[18:33]
	v_mfma_f32_32x32x16_bf16 v[34:49], v[66:69], v[78:81], v[34:49]
	v_mfma_f32_32x32x16_bf16 v[2:17], v[70:73], v[78:81], v[2:17]
	s_setprio 0
	ds_read_b128 v[66:69], v89
	ds_read_b128 v[70:73], v89 offset:4096
	ds_read_b128 v[74:77], v131 offset:32768
	ds_read_b128 v[78:81], v131 offset:36864
	s_waitcnt lgkmcnt(4)
	s_setprio 1
	v_mfma_f32_32x32x16_bf16 v[50:65], v[154:157], v[162:165], v[50:65]
	v_mfma_f32_32x32x16_bf16 v[18:33], v[158:161], v[162:165], v[18:33]
	v_mfma_f32_32x32x16_bf16 v[34:49], v[154:157], v[166:169], v[34:49]
	v_mfma_f32_32x32x16_bf16 v[2:17], v[158:161], v[166:169], v[2:17]
	s_setprio 0
	s_waitcnt lgkmcnt(0)
	s_setprio 1
	v_mfma_f32_32x32x16_bf16 v[50:65], v[66:69], v[74:77], v[50:65]
	v_mfma_f32_32x32x16_bf16 v[18:33], v[70:73], v[74:77], v[18:33]
	v_mfma_f32_32x32x16_bf16 v[34:49], v[66:69], v[78:81], v[34:49]
	v_mfma_f32_32x32x16_bf16 v[2:17], v[70:73], v[78:81], v[2:17]
	s_setprio 0
	s_add_i32 s20, s20, 1
	s_cmp_eq_u32 s20, 3
	s_cselect_b32 vcc_lo, 0xfffdc000, 0
	s_cselect_b32 s20, 0, s20
	s_add_i32 vcc_lo, vcc_lo, 0xc000
	v_add_u32_e32 v86, vcc_lo, v86
	v_add_u32_e32 v128, vcc_lo, v128
	v_add_u32_e32 v87, vcc_lo, v87
	v_add_u32_e32 v129, vcc_lo, v129
	v_add_u32_e32 v88, vcc_lo, v88
	v_add_u32_e32 v130, vcc_lo, v130
	v_add_u32_e32 v89, vcc_lo, v89
	v_add_u32_e32 v131, vcc_lo, v131
	s_waitcnt vmcnt(0)
	s_barrier
	ds_read_b128 v[154:157], v86
	ds_read_b128 v[158:161], v86 offset:4096
	ds_read_b128 v[162:165], v128 offset:32768
	ds_read_b128 v[166:169], v128 offset:36864
	ds_read_b128 v[66:69], v87
	ds_read_b128 v[70:73], v87 offset:4096
	ds_read_b128 v[74:77], v129 offset:32768
	ds_read_b128 v[78:81], v129 offset:36864
	s_waitcnt lgkmcnt(4)
	s_setprio 1
	v_mfma_f32_32x32x16_bf16 v[50:65], v[154:157], v[162:165], v[50:65]
	v_mfma_f32_32x32x16_bf16 v[18:33], v[158:161], v[162:165], v[18:33]
	v_mfma_f32_32x32x16_bf16 v[34:49], v[154:157], v[166:169], v[34:49]
	v_mfma_f32_32x32x16_bf16 v[2:17], v[158:161], v[166:169], v[2:17]
	s_setprio 0
	ds_read_b128 v[154:157], v88
	ds_read_b128 v[158:161], v88 offset:4096
	ds_read_b128 v[162:165], v130 offset:32768
	ds_read_b128 v[166:169], v130 offset:36864
	s_waitcnt lgkmcnt(4)
	s_setprio 1
	v_mfma_f32_32x32x16_bf16 v[50:65], v[66:69], v[74:77], v[50:65]
	v_mfma_f32_32x32x16_bf16 v[18:33], v[70:73], v[74:77], v[18:33]
	v_mfma_f32_32x32x16_bf16 v[34:49], v[66:69], v[78:81], v[34:49]
	v_mfma_f32_32x32x16_bf16 v[2:17], v[70:73], v[78:81], v[2:17]
	s_setprio 0
	ds_read_b128 v[66:69], v89
	ds_read_b128 v[70:73], v89 offset:4096
	ds_read_b128 v[74:77], v131 offset:32768
	ds_read_b128 v[78:81], v131 offset:36864
	s_waitcnt lgkmcnt(4)
	s_setprio 1
	v_mfma_f32_32x32x16_bf16 v[50:65], v[154:157], v[162:165], v[50:65]
	v_mfma_f32_32x32x16_bf16 v[18:33], v[158:161], v[162:165], v[18:33]
	v_mfma_f32_32x32x16_bf16 v[34:49], v[154:157], v[166:169], v[34:49]
	v_mfma_f32_32x32x16_bf16 v[2:17], v[158:161], v[166:169], v[2:17]
	s_setprio 0
	s_waitcnt lgkmcnt(0)
	s_setprio 1
	v_mfma_f32_32x32x16_bf16 v[50:65], v[66:69], v[74:77], v[50:65]
	v_mfma_f32_32x32x16_bf16 v[18:33], v[70:73], v[74:77], v[18:33]
	v_mfma_f32_32x32x16_bf16 v[34:49], v[66:69], v[78:81], v[34:49]
	v_mfma_f32_32x32x16_bf16 v[2:17], v[70:73], v[78:81], v[2:17]
	s_setprio 0
	s_barrier
	s_nop 7
	v_add_u32_e32 v68, s40, v142
	v_add_u32_e32 v66, 0xfffff000, v68
	v_lshrrev_b32_e32 v67, 11, v66
	s_movk_i32 s4, 0x1800
	s_movk_i32 s22, 0xfff
	v_mad_u32_u24 v153, v67, s4, s4
	v_cmp_lt_i32_e32 vcc, s22, v68
	v_ashrrev_i32_e32 v69, 31, v68
	v_readlane_b32 s4, v254, 0
	v_or_b32_e32 v66, s42, v143
	v_cndmask_b32_e32 v158, 0, v153, vcc
	v_lshlrev_b64 v[70:71], 12, v[68:69]
	v_readlane_b32 s5, v254, 1
	v_ashrrev_i32_e32 v67, 31, v66
	s_nop 0
	v_lshl_add_u64 v[72:73], s[4:5], 0, v[70:71]
	v_add_u32_e32 v70, v158, v66
	v_ashrrev_i32_e32 v71, 31, v70
	v_lshl_add_u64 v[70:71], v[70:71], 2, s[28:29]
	s_barrier
	global_load_dword v69, v[70:71], off
	v_lshlrev_b64 v[70:71], 2, v[66:67]
	v_lshl_add_u64 v[74:75], v[72:73], 0, v[70:71]
	v_mov_b32_e32 v111, v1
	v_lshl_add_u64 v[72:73], v[74:75], 0, v[0:1]
	v_mov_b32_e32 v99, v1
	v_mov_b32_e32 v101, v1
	v_mov_b32_e32 v103, v1
	v_mov_b32_e32 v105, v1
	v_mov_b32_e32 v107, v1
	v_mov_b32_e32 v109, v1
	v_lshl_add_u64 v[88:89], v[74:75], 0, v[110:111]
	v_mov_b32_e32 v113, v1
	v_lshl_add_u64 v[76:77], v[74:75], 0, v[98:99]
	v_lshl_add_u64 v[78:79], v[74:75], 0, v[100:101]
	v_lshl_add_u64 v[80:81], v[74:75], 0, v[102:103]
	v_lshl_add_u64 v[82:83], v[74:75], 0, v[104:105]
	v_lshl_add_u64 v[84:85], v[74:75], 0, v[106:107]
	v_lshl_add_u64 v[86:87], v[74:75], 0, v[108:109]
	global_load_dword v67, v[72:73], off
	global_load_dword v159, v[76:77], off
	global_load_dword v160, v[78:79], off
	global_load_dword v161, v[80:81], off
	global_load_dword v162, v[82:83], off
	global_load_dword v163, v[84:85], off
	global_load_dword v164, v[86:87], off
	global_load_dword v165, v[88:89], off
	v_lshl_add_u64 v[128:129], v[74:75], 0, v[112:113]
	v_mov_b32_e32 v115, v1
	global_load_dword v166, v[128:129], off
	v_lshl_add_u64 v[130:131], v[74:75], 0, v[114:115]
	v_mov_b32_e32 v117, v1
	global_load_dword v167, v[130:131], off
	v_lshl_add_u64 v[132:133], v[74:75], 0, v[116:117]
	v_mov_b32_e32 v119, v1
	global_load_dword v168, v[132:133], off
	v_lshl_add_u64 v[134:135], v[74:75], 0, v[118:119]
	v_mov_b32_e32 v121, v1
	global_load_dword v169, v[134:135], off
	v_lshl_add_u64 v[136:137], v[74:75], 0, v[120:121]
	v_mov_b32_e32 v123, v1
	global_load_dword v170, v[136:137], off
	v_lshl_add_u64 v[138:139], v[74:75], 0, v[122:123]
	v_mov_b32_e32 v125, v1
	global_load_dword v171, v[138:139], off
	global_load_dword v175, v[72:73], off offset:128
	v_lshl_add_u64 v[154:155], v[74:75], 0, v[124:125]
	v_mov_b32_e32 v127, v1
	global_load_dword v172, v[154:155], off
	v_lshl_add_u64 v[156:157], v[74:75], 0, v[126:127]
	global_load_dword v173, v[156:157], off
	v_add_f32_e32 v50, 0, v50
	v_readlane_b32 s8, v254, 4
	v_readlane_b32 s9, v254, 5
	v_add_f32_e32 v51, 0, v51
	v_add_f32_e32 v52, 0, v52
	v_add_f32_e32 v53, 0, v53
	v_add_f32_e32 v54, 0, v54
	v_add_f32_e32 v55, 0, v55
	v_add_f32_e32 v56, 0, v56
	v_or_b32_e32 v174, 32, v66
	s_mov_b64 s[8:9], 0x80
	v_add_f32_e32 v34, 0, v34
	v_add_f32_e32 v35, 0, v35
	v_add_f32_e32 v36, 0, v36
	v_add_f32_e32 v37, 0, v37
	v_add_f32_e32 v38, 0, v38
	v_add_f32_e32 v39, 0, v39
	v_add_f32_e32 v40, 0, v40
	v_add_f32_e32 v18, 0, v18
	v_add_f32_e32 v19, 0, v19
	v_add_f32_e32 v20, 0, v20
	v_add_f32_e32 v21, 0, v21
	v_add_f32_e32 v2, 0, v2
	s_add_i32 s1, s1, s0
	v_readlane_b32 s6, v254, 2
	v_readlane_b32 s7, v254, 3
	v_add_f32_e32 v3, 0, v3
	v_add_f32_e32 v4, 0, v4
	s_cmpk_gt_i32 s1, 0xff
	v_readlane_b32 s10, v254, 6
	v_readlane_b32 s11, v254, 7
	v_readlane_b32 s12, v254, 8
	v_readlane_b32 s13, v254, 9
	v_readlane_b32 s14, v254, 10
	v_readlane_b32 s15, v254, 11
	v_readlane_b32 s16, v254, 12
	v_readlane_b32 s17, v254, 13
	v_readlane_b32 s18, v254, 14
	v_readlane_b32 s19, v254, 15
	s_waitcnt vmcnt(16)
	v_fmac_f32_e32 v67, v50, v69
	v_add_f32_e32 v50, 0, v57
	s_waitcnt vmcnt(15)
	v_fmac_f32_e32 v159, v51, v69
	s_waitcnt vmcnt(14)
	v_fmac_f32_e32 v160, v52, v69
	s_waitcnt vmcnt(13)
	v_fmac_f32_e32 v161, v53, v69
	s_waitcnt vmcnt(12)
	v_fmac_f32_e32 v162, v54, v69
	s_waitcnt vmcnt(11)
	v_fmac_f32_e32 v163, v55, v69
	s_waitcnt vmcnt(9)
	v_fmac_f32_e32 v165, v50, v69
	v_add_f32_e32 v50, 0, v58
	v_fmac_f32_e32 v164, v56, v69
	s_waitcnt vmcnt(8)
	v_fmac_f32_e32 v166, v50, v69
	v_add_f32_e32 v50, 0, v59
	global_store_dword v[72:73], v67, off
	global_store_dword v[76:77], v159, off
	global_store_dword v[78:79], v160, off
	global_store_dword v[80:81], v161, off
	global_store_dword v[82:83], v162, off
	global_store_dword v[84:85], v163, off
	global_store_dword v[86:87], v164, off
	s_waitcnt vmcnt(14)
	v_fmac_f32_e32 v167, v50, v69
	v_add_f32_e32 v50, 0, v60
	v_add_f32_e32 v67, 0, v65
	s_waitcnt vmcnt(13)
	v_fmac_f32_e32 v168, v50, v69
	v_add_f32_e32 v50, 0, v61
	global_store_dword v[88:89], v165, off
	s_waitcnt vmcnt(13)
	v_fmac_f32_e32 v169, v50, v69
	v_add_f32_e32 v50, 0, v62
	global_store_dword v[128:129], v166, off
	s_waitcnt vmcnt(13)
	v_fmac_f32_e32 v170, v50, v69
	v_add_f32_e32 v50, 0, v63
	global_store_dword v[130:131], v167, off
	s_waitcnt vmcnt(13)
	v_fmac_f32_e32 v171, v50, v69
	v_add_f32_e32 v50, 0, v64
	global_store_dword v[132:133], v168, off
	global_store_dword v[134:135], v169, off
	s_waitcnt vmcnt(13)
	v_fmac_f32_e32 v172, v50, v69
	v_lshl_add_u64 v[50:51], v[74:75], 0, s[8:9]
	v_add_u32_e32 v74, v158, v174
	global_store_dword v[136:137], v170, off
	global_store_dword v[138:139], v171, off
	global_store_dword v[154:155], v172, off
	v_lshl_add_u64 v[52:53], v[50:51], 0, v[98:99]
	s_waitcnt vmcnt(15)
	v_fmac_f32_e32 v173, v67, v69
	v_ashrrev_i32_e32 v75, 31, v74
	v_lshl_add_u64 v[54:55], v[50:51], 0, v[100:101]
	v_lshl_add_u64 v[56:57], v[50:51], 0, v[102:103]
	v_lshl_add_u64 v[58:59], v[50:51], 0, v[104:105]
	v_lshl_add_u64 v[60:61], v[50:51], 0, v[106:107]
	v_lshl_add_u64 v[62:63], v[50:51], 0, v[108:109]
	v_lshl_add_u64 v[64:65], v[50:51], 0, v[110:111]
	global_load_dword v88, v[52:53], off
	global_load_dword v89, v[54:55], off
	global_load_dword v128, v[56:57], off
	global_load_dword v129, v[58:59], off
	global_load_dword v130, v[60:61], off
	global_load_dword v131, v[62:63], off
	global_load_dword v132, v[64:65], off
	v_lshl_add_u64 v[74:75], v[74:75], 2, s[28:29]
	global_store_dword v[156:157], v173, off
	global_load_dword v67, v[74:75], off
	v_lshl_add_u64 v[74:75], v[50:51], 0, v[112:113]
	global_load_dword v69, v[74:75], off
	v_lshl_add_u64 v[76:77], v[50:51], 0, v[114:115]
	global_load_dword v133, v[76:77], off
	v_lshl_add_u64 v[78:79], v[50:51], 0, v[116:117]
	global_load_dword v134, v[78:79], off
	v_lshl_add_u64 v[80:81], v[50:51], 0, v[118:119]
	global_load_dword v135, v[80:81], off
	v_lshl_add_u64 v[82:83], v[50:51], 0, v[120:121]
	global_load_dword v136, v[82:83], off
	v_lshl_add_u64 v[84:85], v[50:51], 0, v[122:123]
	global_load_dword v137, v[84:85], off
	v_lshl_add_u64 v[86:87], v[50:51], 0, v[124:125]
	global_load_dword v138, v[86:87], off
	v_lshl_add_u64 v[50:51], v[50:51], 0, v[126:127]
	global_load_dword v139, v[50:51], off
	s_waitcnt vmcnt(8)
	v_fmac_f32_e32 v175, v34, v67
	v_add_f32_e32 v34, 0, v41
	v_fmac_f32_e32 v132, v34, v67
	v_add_f32_e32 v34, 0, v42
	s_waitcnt vmcnt(7)
	v_fmac_f32_e32 v69, v34, v67
	v_add_f32_e32 v34, 0, v43
	s_waitcnt vmcnt(6)
	v_fmac_f32_e32 v133, v34, v67
	v_add_f32_e32 v34, 0, v44
	s_waitcnt vmcnt(5)
	v_fmac_f32_e32 v134, v34, v67
	v_add_f32_e32 v34, 0, v45
	s_waitcnt vmcnt(4)
	v_fmac_f32_e32 v135, v34, v67
	v_add_f32_e32 v34, 0, v46
	s_waitcnt vmcnt(3)
	v_fmac_f32_e32 v136, v34, v67
	v_add_f32_e32 v34, 0, v47
	s_waitcnt vmcnt(2)
	v_fmac_f32_e32 v137, v34, v67
	v_add_f32_e32 v34, 0, v48
	s_waitcnt vmcnt(1)
	v_fmac_f32_e32 v138, v34, v67
	v_add_f32_e32 v34, 0, v49
	s_waitcnt vmcnt(0)
	v_fmac_f32_e32 v139, v34, v67
	v_or_b32_e32 v34, 32, v68
	v_cmp_lt_i32_e32 vcc, s22, v34
	v_fmac_f32_e32 v88, v35, v67
	v_ashrrev_i32_e32 v35, 31, v34
	v_cndmask_b32_e32 v68, 0, v153, vcc
	v_fmac_f32_e32 v89, v36, v67
	v_lshlrev_b64 v[34:35], 12, v[34:35]
	v_add_u32_e32 v36, v68, v66
	v_fmac_f32_e32 v128, v37, v67
	v_lshl_add_u64 v[34:35], s[4:5], 0, v[34:35]
	v_ashrrev_i32_e32 v37, 31, v36
	v_fmac_f32_e32 v129, v38, v67
	v_fmac_f32_e32 v130, v39, v67
	v_fmac_f32_e32 v131, v40, v67
	global_store_dword v[72:73], v175, off offset:128
	global_store_dword v[52:53], v88, off
	global_store_dword v[54:55], v89, off
	global_store_dword v[56:57], v128, off
	global_store_dword v[58:59], v129, off
	global_store_dword v[60:61], v130, off
	global_store_dword v[62:63], v131, off
	global_store_dword v[64:65], v132, off
	global_store_dword v[74:75], v69, off
	global_store_dword v[76:77], v133, off
	global_store_dword v[78:79], v134, off
	global_store_dword v[80:81], v135, off
	global_store_dword v[82:83], v136, off
	global_store_dword v[84:85], v137, off
	global_store_dword v[86:87], v138, off
	global_store_dword v[50:51], v139, off
	v_lshl_add_u64 v[36:37], v[36:37], 2, s[28:29]
	v_lshl_add_u64 v[34:35], v[34:35], 0, v[70:71]
	global_load_dword v69, v[36:37], off
	v_lshl_add_u64 v[36:37], v[34:35], 0, v[0:1]
	v_lshl_add_u64 v[42:43], v[34:35], 0, v[102:103]
	v_lshl_add_u64 v[44:45], v[34:35], 0, v[104:105]
	v_lshl_add_u64 v[38:39], v[34:35], 0, v[98:99]
	v_lshl_add_u64 v[40:41], v[34:35], 0, v[100:101]
	global_load_dword v70, v[36:37], off
	global_load_dword v71, v[38:39], off
	global_load_dword v72, v[40:41], off
	global_load_dword v73, v[42:43], off
	global_load_dword v74, v[44:45], off
	v_lshl_add_u64 v[46:47], v[34:35], 0, v[106:107]
	global_load_dword v75, v[46:47], off
	v_lshl_add_u64 v[48:49], v[34:35], 0, v[108:109]
	global_load_dword v76, v[48:49], off
	v_lshl_add_u64 v[50:51], v[34:35], 0, v[110:111]
	global_load_dword v77, v[50:51], off
	v_lshl_add_u64 v[52:53], v[34:35], 0, v[112:113]
	global_load_dword v78, v[52:53], off
	v_lshl_add_u64 v[54:55], v[34:35], 0, v[114:115]
	global_load_dword v79, v[54:55], off
	global_load_dword v86, v[36:37], off offset:128
	v_lshl_add_u64 v[56:57], v[34:35], 0, v[116:117]
	global_load_dword v80, v[56:57], off
	v_lshl_add_u64 v[58:59], v[34:35], 0, v[118:119]
	global_load_dword v81, v[58:59], off
	v_lshl_add_u64 v[60:61], v[34:35], 0, v[120:121]
	global_load_dword v82, v[60:61], off
	v_lshl_add_u64 v[62:63], v[34:35], 0, v[122:123]
	global_load_dword v83, v[62:63], off
	v_lshl_add_u64 v[64:65], v[34:35], 0, v[124:125]
	global_load_dword v84, v[64:65], off
	v_lshl_add_u64 v[66:67], v[34:35], 0, v[126:127]
	global_load_dword v85, v[66:67], off
	s_waitcnt vmcnt(16)
	v_fmac_f32_e32 v70, v18, v69
	v_add_f32_e32 v18, 0, v22
	s_waitcnt vmcnt(15)
	v_fmac_f32_e32 v71, v19, v69
	s_waitcnt vmcnt(14)
	v_fmac_f32_e32 v72, v20, v69
	s_waitcnt vmcnt(12)
	v_fmac_f32_e32 v74, v18, v69
	v_add_f32_e32 v18, 0, v23
	s_waitcnt vmcnt(11)
	v_fmac_f32_e32 v75, v18, v69
	v_add_f32_e32 v18, 0, v24
	s_waitcnt vmcnt(10)
	v_fmac_f32_e32 v76, v18, v69
	v_add_f32_e32 v18, 0, v25
	s_waitcnt vmcnt(9)
	v_fmac_f32_e32 v77, v18, v69
	v_add_f32_e32 v18, 0, v26
	s_waitcnt vmcnt(8)
	v_fmac_f32_e32 v78, v18, v69
	v_add_f32_e32 v18, 0, v27
	s_waitcnt vmcnt(7)
	v_fmac_f32_e32 v79, v18, v69
	v_add_f32_e32 v18, 0, v28
	global_store_dword v[36:37], v70, off
	global_store_dword v[38:39], v71, off
	global_store_dword v[40:41], v72, off
	s_waitcnt vmcnt(8)
	v_fmac_f32_e32 v80, v18, v69
	v_add_f32_e32 v18, 0, v29
	s_waitcnt vmcnt(7)
	v_fmac_f32_e32 v81, v18, v69
	v_add_f32_e32 v18, 0, v30
	s_waitcnt vmcnt(6)
	v_fmac_f32_e32 v82, v18, v69
	v_add_f32_e32 v18, 0, v31
	s_waitcnt vmcnt(5)
	v_fmac_f32_e32 v83, v18, v69
	v_add_f32_e32 v18, 0, v32
	v_fmac_f32_e32 v73, v21, v69
	s_waitcnt vmcnt(4)
	v_fmac_f32_e32 v84, v18, v69
	v_add_f32_e32 v38, 0, v33
	v_lshl_add_u64 v[18:19], v[34:35], 0, s[8:9]
	v_add_u32_e32 v34, v68, v174
	global_store_dword v[42:43], v73, off
	global_store_dword v[44:45], v74, off
	global_store_dword v[46:47], v75, off
	global_store_dword v[48:49], v76, off
	global_store_dword v[50:51], v77, off
	global_store_dword v[52:53], v78, off
	global_store_dword v[54:55], v79, off
	global_store_dword v[56:57], v80, off
	global_store_dword v[58:59], v81, off
	global_store_dword v[60:61], v82, off
	global_store_dword v[62:63], v83, off
	global_store_dword v[64:65], v84, off
	v_lshl_add_u64 v[20:21], v[18:19], 0, v[98:99]
	s_waitcnt vmcnt(15)
	v_fmac_f32_e32 v85, v38, v69
	v_ashrrev_i32_e32 v35, 31, v34
	v_lshl_add_u64 v[22:23], v[18:19], 0, v[100:101]
	v_lshl_add_u64 v[24:25], v[18:19], 0, v[102:103]
	v_lshl_add_u64 v[26:27], v[18:19], 0, v[104:105]
	v_lshl_add_u64 v[28:29], v[18:19], 0, v[106:107]
	v_lshl_add_u64 v[30:31], v[18:19], 0, v[108:109]
	v_lshl_add_u64 v[32:33], v[18:19], 0, v[110:111]
	global_load_dword v50, v[20:21], off
	global_load_dword v51, v[22:23], off
	global_load_dword v52, v[24:25], off
	global_load_dword v53, v[26:27], off
	global_load_dword v54, v[28:29], off
	global_load_dword v55, v[30:31], off
	global_load_dword v56, v[32:33], off
	v_lshl_add_u64 v[34:35], v[34:35], 2, s[28:29]
	global_store_dword v[66:67], v85, off
	global_load_dword v57, v[34:35], off
	v_lshl_add_u64 v[34:35], v[18:19], 0, v[112:113]
	global_load_dword v58, v[34:35], off
	v_lshl_add_u64 v[38:39], v[18:19], 0, v[114:115]
	global_load_dword v59, v[38:39], off
	v_lshl_add_u64 v[40:41], v[18:19], 0, v[116:117]
	global_load_dword v60, v[40:41], off
	v_lshl_add_u64 v[42:43], v[18:19], 0, v[118:119]
	global_load_dword v61, v[42:43], off
	v_lshl_add_u64 v[44:45], v[18:19], 0, v[120:121]
	global_load_dword v62, v[44:45], off
	v_lshl_add_u64 v[46:47], v[18:19], 0, v[122:123]
	global_load_dword v63, v[46:47], off
	v_lshl_add_u64 v[48:49], v[18:19], 0, v[124:125]
	global_load_dword v64, v[48:49], off
	v_lshl_add_u64 v[18:19], v[18:19], 0, v[126:127]
	global_load_dword v65, v[18:19], off
	s_waitcnt vmcnt(8)
	v_fmac_f32_e32 v86, v2, v57
	v_add_f32_e32 v2, 0, v5
	v_fmac_f32_e32 v52, v2, v57
	v_add_f32_e32 v2, 0, v6
	v_fmac_f32_e32 v53, v2, v57
	v_add_f32_e32 v2, 0, v7
	v_fmac_f32_e32 v54, v2, v57
	v_add_f32_e32 v2, 0, v8
	v_fmac_f32_e32 v55, v2, v57
	v_add_f32_e32 v2, 0, v9
	v_fmac_f32_e32 v56, v2, v57
	v_add_f32_e32 v2, 0, v10
	s_waitcnt vmcnt(7)
	v_fmac_f32_e32 v58, v2, v57
	v_add_f32_e32 v2, 0, v11
	s_waitcnt vmcnt(6)
	v_fmac_f32_e32 v59, v2, v57
	v_add_f32_e32 v2, 0, v12
	s_waitcnt vmcnt(5)
	v_fmac_f32_e32 v60, v2, v57
	v_add_f32_e32 v2, 0, v13
	s_waitcnt vmcnt(4)
	v_fmac_f32_e32 v61, v2, v57
	v_add_f32_e32 v2, 0, v14
	s_waitcnt vmcnt(3)
	v_fmac_f32_e32 v62, v2, v57
	v_add_f32_e32 v2, 0, v15
	s_waitcnt vmcnt(2)
	v_fmac_f32_e32 v63, v2, v57
	v_add_f32_e32 v2, 0, v16
	s_waitcnt vmcnt(1)
	v_fmac_f32_e32 v64, v2, v57
	v_add_f32_e32 v2, 0, v17
	s_waitcnt vmcnt(0)
	v_fmac_f32_e32 v65, v2, v57
	v_fmac_f32_e32 v50, v3, v57
	v_fmac_f32_e32 v51, v4, v57
	global_store_dword v[36:37], v86, off offset:128
	global_store_dword v[20:21], v50, off
	global_store_dword v[22:23], v51, off
	global_store_dword v[24:25], v52, off
	global_store_dword v[26:27], v53, off
	global_store_dword v[28:29], v54, off
	global_store_dword v[30:31], v55, off
	global_store_dword v[32:33], v56, off
	global_store_dword v[34:35], v58, off
	global_store_dword v[38:39], v59, off
	global_store_dword v[40:41], v60, off
	global_store_dword v[42:43], v61, off
	global_store_dword v[44:45], v62, off
	global_store_dword v[46:47], v63, off
	global_store_dword v[48:49], v64, off
	global_store_dword v[18:19], v65, off
	s_cbranch_scc0 .LBB0_424
